# mixer work queue: next ticket's atomic issued one item ahead and parked in v255 (next_free_vgpr 256), ticket broadcast through LDS with ds ops
# baseline (speedup 1.0000x reference)
; DEV int otid() { int t = threadIdx.x; asm volatile("" : "+v"(t)); return t; }
; DEV void phase2(const Params& p, int rerun) {
;   const int tidx = otid();
;   const int parts = rerun ? PROBE_PART : 7;
;   if (parts & 1) for (int g = blockIdx.x; g < 64; g += gridDim.x) gla_block(p, g);
;   unsigned* ctr = (unsigned*)(p.ws + OFF_MISC + (rerun ? 256 : 0));
;   volatile int* slot = (volatile int*)(smem + 131072 + 2048);
;   unsigned* mkv_done = (unsigned*)(p.ws + OFF_MISC + 1024);
;   const int nstatic = ((parts & 1) && gridDim.x > 64) ? (int)gridDim.x - 64 : ((parts & 1) ? 0 : (int)gridDim.x);
;   bool first = ((parts & 1) ? (int)blockIdx.x >= 64 && nstatic > 0 : true);
;   const int firstit = (parts & 1) ? (int)blockIdx.x - 64 : (int)blockIdx.x;
.LBB0_349:
	s_load_dword s5, s[84:85], 0x10
	s_and_b64 s[0:1], exec, s[0:1]
	s_cselect_b32 s0, 0, 0x100
	v_readlane_b32 s1, v253, 31
	s_add_u32 s6, s1, s0
	v_readlane_b32 s0, v253, 32
	s_addc_u32 s7, s0, 0
	s_waitcnt lgkmcnt(0)
	s_lshr_b32 s0, s5, 16
	s_and_b32 s0, s0, 0xffff
	s_cmp_lg_u32 s0, 0
	s_cselect_b64 s[0:1], -1, 0
	v_writelane_b32 v254, s6, 56
	s_cmp_lg_u64 s[0:1], 0
	s_addc_u32 s33, s4, 0
	v_writelane_b32 v254, s7, 57
	v_sub_u32_e64 v200, s33, 64 clamp
	v_readlane_b32 s0, v253, 23
	v_cmp_eq_u32_e64 s[66:67], 0, v223
	v_writelane_b32 v254, s33, 58
	v_cmp_lt_i32_e32 vcc, 0, v200
	v_readlane_b32 s1, v253, 24
	v_writelane_b32 v254, s66, 59
	s_and_b64 s[4:5], s[0:1], vcc
	s_mov_b32 s65, 0x800000
	v_writelane_b32 v254, s67, 60
	v_mov_b32_e32 v255, -1
	s_branch .LBB0_444

; DEV void phase2(const Params& p, int rerun) {
;     ...
;   while (true) {
;     __syncthreads();
;     if (tidx == 0) *slot = first ? firstit : (int)(nstatic + atomicAdd(ctr, 1u));
;     first = false;
;     __syncthreads();
;     const int it = __builtin_amdgcn_readfirstlane(*slot);
;     if (it >= 64 + 512 + 128) break;
;     if (it < 64) {
;       phase1(p, 2816 + it);
;       __threadfence();
;       __syncthreads();
;       if (tidx == 0) atomicAdd(mkv_done, 1u);
;     } else if (it < 64 + 320) { if (parts & 2) sb_block(p, it - 64); }
;     else if (it >= 64 + 320 + 128) { if (parts & 2) sb_block(p, it - 64 - 128); }
;     else {
;       if (tidx == 0) {
;         while (__hip_atomic_load(mkv_done, __ATOMIC_RELAXED, __HIP_MEMORY_SCOPE_AGENT) < 64u) __builtin_amdgcn_s_sleep(8);
;         __builtin_amdgcn_fence(__ATOMIC_ACQUIRE, "agent");
.LBB0_444:
	s_barrier
	s_and_saveexec_b64 s[0:1], s[66:67]
	s_cbranch_execz .LBB0_450
	s_xor_b64 s[4:5], s[4:5], -1
	s_andn2_b64 vcc, exec, s[4:5]
	v_readlane_b32 s4, v253, 35
	s_nop 1
	v_mov_b32_e32 v0, s4
	s_cbranch_vccz .Lqm_notfirst
	v_readlane_b32 s6, v254, 56
	v_readlane_b32 s7, v254, 57
	v_mov_b32_e32 v255, 1
	s_nop 4
	global_atomic_add v255, v177, v255, s[6:7] sc0
	s_branch .LBB0_449
	s_nop 0
	s_nop 0
	s_nop 0
	s_nop 0
	s_nop 0
	s_nop 0
	s_nop 0
.Lqm_notfirst:
	s_mov_b64 s[6:7], exec
	v_mbcnt_lo_u32_b32 v0, s6, 0
	v_mbcnt_hi_u32_b32 v0, s7, v0
	v_cmp_eq_u32_e32 vcc, 0, v0
	s_and_saveexec_b64 s[4:5], vcc
	s_cbranch_execz .LBB0_448
	v_readlane_b32 s6, v254, 56
	v_readlane_b32 s7, v254, 57
	s_waitcnt vmcnt(0)
	s_nop 0
	v_readfirstlane_b32 s71, v255
	s_cmp_lg_u32 s71, -1
	s_cbranch_scc1 .Lqm_have
	v_mov_b32_e32 v255, 1
	s_nop 4
	global_atomic_add v255, v177, v255, s[6:7] sc0
	s_waitcnt vmcnt(0)
.Lqm_have:
	v_mov_b32_e32 v1, v255
	v_mov_b32_e32 v255, 1
	s_nop 4
	global_atomic_add v255, v177, v255, s[6:7] sc0
.LBB0_448:
	s_or_b64 exec, exec, s[4:5]
	s_nop 0
	v_readfirstlane_b32 s4, v1
	s_nop 1
	v_add_u32_e32 v1, s4, v200
	v_add_u32_e32 v0, v1, v0
.LBB0_449:
	v_mov_b32_e32 v2, 0x20800
	ds_write_b32 v2, v0
	s_waitcnt lgkmcnt(0)
.LBB0_450:
	s_or_b64 exec, exec, s[0:1]
	s_add_i32 s71, 0, 0x20800
	v_mov_b32_e32 v0, 0x20800
	s_waitcnt lgkmcnt(0)
	s_barrier
	ds_read_b32 v0, v0
	s_mov_b64 s[0:1], -1
	s_waitcnt lgkmcnt(0)
	v_readfirstlane_b32 s28, v0
	s_cmpk_gt_i32 s28, 0x2bf
	s_cbranch_scc1 .LBB0_443
	s_cmp_gt_i32 s28, 63
	s_cbranch_scc0 .LBB0_576
	s_cmpk_gt_u32 s28, 0x17f
	s_cbranch_scc0 .LBB0_483
	s_cmpk_lt_u32 s28, 0x200
	s_cbranch_scc0 .LBB0_474
	s_and_saveexec_b64 s[0:1], s[66:67]
	s_cbranch_execz .LBB0_458
	v_readlane_b32 s4, v253, 33
	v_readlane_b32 s5, v253, 34
	s_nop 4
	global_load_dword v0, v177, s[4:5] sc1
	s_waitcnt vmcnt(0)
	v_cmp_lt_u32_e32 vcc, 63, v0
	s_cbranch_vccnz .LBB0_457

; __global__ void __launch_bounds__(512) hybrid_layer_megakernel(Params p, int ph_lo, int ph_hi) {
	.amdhsa_kernel _Z23hybrid_layer_megakernel6Paramsii
		.amdhsa_group_segment_fixed_size 0
		.amdhsa_private_segment_fixed_size 0
		.amdhsa_kernarg_size 392
		.amdhsa_user_sgpr_count 2
		.amdhsa_user_sgpr_dispatch_ptr 0
		.amdhsa_user_sgpr_queue_ptr 0
		.amdhsa_user_sgpr_kernarg_segment_ptr 1
		.amdhsa_user_sgpr_dispatch_id 0
		.amdhsa_user_sgpr_kernarg_preload_length 0
		.amdhsa_user_sgpr_kernarg_preload_offset 0
		.amdhsa_user_sgpr_private_segment_size 0
		.amdhsa_uses_dynamic_stack 0
		.amdhsa_enable_private_segment 0
		.amdhsa_system_sgpr_workgroup_id_x 1
		.amdhsa_system_sgpr_workgroup_id_y 0
		.amdhsa_system_sgpr_workgroup_id_z 0
		.amdhsa_system_sgpr_workgroup_info 0
		.amdhsa_system_vgpr_workitem_id 2
		.amdhsa_next_free_vgpr 256
		.amdhsa_next_free_sgpr 100
		.amdhsa_accum_offset 256
		.amdhsa_reserve_vcc 1
		.amdhsa_float_round_mode_32 0
		.amdhsa_float_round_mode_16_64 0
		.amdhsa_float_denorm_mode_32 3
		.amdhsa_float_denorm_mode_16_64 3
		.amdhsa_dx10_clamp 1
		.amdhsa_ieee_mode 1
		.amdhsa_fp16_overflow 0
		.amdhsa_tg_split 0
		.amdhsa_exception_fp_ieee_invalid_op 0
		.amdhsa_exception_fp_denorm_src 0
		.amdhsa_exception_fp_ieee_div_zero 0
		.amdhsa_exception_fp_ieee_overflow 0
		.amdhsa_exception_fp_ieee_underflow 0
		.amdhsa_exception_fp_ieee_inexact 0
		.amdhsa_exception_int_div_zero 0
	.end_amdhsa_kernel

; __global__ void __launch_bounds__(512) hybrid_layer_megakernel(Params p, int ph_lo, int ph_hi) {
amdhsa.kernels:
  - .agpr_count:     0
    .args:
      - .offset:         0
        .size:           128
        .value_kind:     by_value
      - .offset:         128
        .size:           4
        .value_kind:     by_value
      - .offset:         132
        .size:           4
        .value_kind:     by_value
      - .offset:         136
        .size:           4
        .value_kind:     hidden_block_count_x
      - .offset:         140
        .size:           4
        .value_kind:     hidden_block_count_y
      - .offset:         144
        .size:           4
        .value_kind:     hidden_block_count_z
      - .offset:         148
        .size:           2
        .value_kind:     hidden_group_size_x
      - .offset:         150
        .size:           2
        .value_kind:     hidden_group_size_y
      - .offset:         152
        .size:           2
        .value_kind:     hidden_group_size_z
      - .offset:         154
        .size:           2
        .value_kind:     hidden_remainder_x
      - .offset:         156
        .size:           2
        .value_kind:     hidden_remainder_y
      - .offset:         158
        .size:           2
        .value_kind:     hidden_remainder_z
      - .offset:         176
        .size:           8
        .value_kind:     hidden_global_offset_x
      - .offset:         184
        .size:           8
        .value_kind:     hidden_global_offset_y
      - .offset:         192
        .size:           8
        .value_kind:     hidden_global_offset_z
      - .offset:         200
        .size:           2
        .value_kind:     hidden_grid_dims
      - .offset:         224
        .size:           8
        .value_kind:     hidden_multigrid_sync_arg
      - .offset:         256
        .size:           4
        .value_kind:     hidden_dynamic_lds_size
    .group_segment_fixed_size: 0
    .kernarg_segment_align: 8
    .kernarg_segment_size: 392
    .language:       OpenCL C
    .language_version:
      - 2
      - 0
    .max_flat_workgroup_size: 512
    .name:           _Z23hybrid_layer_megakernel6Paramsii
    .private_segment_fixed_size: 0
    .sgpr_count:     106
    .sgpr_spill_count: 170
    .symbol:         _Z23hybrid_layer_megakernel6Paramsii.kd
    .uniform_work_group_size: 1
    .uses_dynamic_stack: false
    .vgpr_count:     256
    .vgpr_spill_count: 0
    .wavefront_size: 64
